# grid barrier release merged into the arrival counter: waiters spin on TOP >= (index+1)*nx, no generation atomics
# speedup vs baseline: 1.0177x; 1.0030x over previous
.LBB0_157:
	s_or_b64 exec, exec, s[10:11]
	v_cvt_f32_u32_e32 v4, v2
	s_waitcnt vmcnt(0)
	v_readfirstlane_b32 s0, v3
	v_sub_u32_e32 v3, 0, v2
	v_rcp_iflag_f32_e32 v4, v4
	v_add_u32_e32 v5, s0, v1
	v_mul_f32_e32 v4, 0x4f7ffffe, v4
	v_cvt_u32_f32_e32 v4, v4
	v_mul_lo_u32 v1, v3, v4
	v_mul_hi_u32 v1, v4, v1
	v_add_u32_e32 v1, v4, v1
	v_mul_hi_u32 v1, v5, v1
	v_mul_lo_u32 v3, v1, v2
	v_sub_u32_e32 v3, v5, v3
	v_add_u32_e32 v4, 1, v1
	v_cmp_ge_u32_e32 vcc, v3, v2
	s_nop 1
	v_cndmask_b32_e32 v1, v1, v4, vcc
	v_sub_u32_e32 v4, v3, v2
	v_cndmask_b32_e32 v3, v3, v4, vcc
	v_add_u32_e32 v4, 1, v1
	v_cmp_ge_u32_e32 vcc, v3, v2
	v_add_u32_e32 v3, 1, v5
	s_nop 0
	v_cndmask_b32_e32 v1, v1, v4, vcc
	v_mul_lo_u32 v4, v2, v1
	v_add_u32_e32 v2, v4, v2
	v_cmp_ne_u32_e32 vcc, v3, v2
	s_and_saveexec_b64 s[0:1], vcc
	s_xor_b64 s[10:11], exec, s[0:1]
	s_cbranch_execz .LBB0_171
	s_waitcnt lgkmcnt(0)
	s_add_u32 s16, s6, 0xe803400
	s_addc_u32 s17, s7, 0
	v_add_u32_e32 v1, 1, v1
	v_mul_lo_u32 v1, v1, v0
	v_mov_b32_e32 v0, 0
	global_load_dword v0, v0, s[16:17] sc1
	s_waitcnt vmcnt(0)
	v_cmp_gt_u32_e32 vcc, v1, v0
	s_and_saveexec_b64 s[12:13], vcc
	s_cbranch_execz .LBB0_170
	s_add_u32 s14, s6, 0xe800200
	s_addc_u32 s15, s7, 0
	s_mov_b32 s2, 1
	s_mov_b64 s[18:19], 0
	v_mov_b32_e32 v0, 0
	s_branch .LBB0_161

.LBB0_163:
	global_load_dword v2, v0, s[16:17] sc1
	s_add_i32 s2, s2, 1
	s_mov_b64 s[24:25], -1
	s_waitcnt vmcnt(0)
	v_cmp_le_u32_e32 vcc, v1, v2
	s_orn2_b64 s[22:23], vcc, exec
	s_branch .LBB0_160

.LBB0_174:
	s_or_b64 exec, exec, s[10:11]
	v_cvt_f32_u32_e32 v3, v0
	s_waitcnt vmcnt(0)
	v_readfirstlane_b32 s0, v2
	s_add_u32 s12, s6, 0xe803400
	s_addc_u32 s13, s7, 0
	v_rcp_iflag_f32_e32 v3, v3
	v_add_u32_e32 v1, s0, v1
	v_add_u32_e32 v4, 1, v1
	s_mov_b64 s[0:1], 0
	v_mul_f32_e32 v2, 0x4f7ffffe, v3
	v_cvt_u32_f32_e32 v2, v2
	v_sub_u32_e32 v3, 0, v0
	v_mul_lo_u32 v3, v3, v2
	v_mul_hi_u32 v3, v2, v3
	v_add_u32_e32 v2, v2, v3
	v_mul_hi_u32 v2, v1, v2
	v_mul_lo_u32 v3, v2, v0
	v_sub_u32_e32 v1, v1, v3
	v_add_u32_e32 v5, 1, v2
	v_cmp_ge_u32_e32 vcc, v1, v0
	v_sub_u32_e32 v3, v1, v0
	s_nop 0
	v_cndmask_b32_e32 v2, v2, v5, vcc
	v_cndmask_b32_e32 v1, v1, v3, vcc
	v_add_u32_e32 v3, 1, v2
	v_cmp_ge_u32_e32 vcc, v1, v0
	s_nop 1
	v_cndmask_b32_e32 v2, v2, v3, vcc
	v_mul_lo_u32 v1, v0, v2
	v_add_u32_e32 v0, v1, v0
	v_cmp_ne_u32_e32 vcc, v4, v0
	v_mov_b32_e32 v2, v0
	v_mov_b64_e32 v[0:1], s[12:13]
	s_and_saveexec_b64 s[10:11], vcc
	s_cbranch_execz .LBB0_186
	v_mov_b32_e32 v0, 0
	global_load_dword v1, v0, s[12:13] sc1
	s_mov_b64 s[0:1], 0
	s_waitcnt vmcnt(0)
	v_cmp_gt_u32_e32 vcc, v2, v1
	s_and_saveexec_b64 s[16:17], vcc
	s_cbranch_execz .LBB0_185
	s_add_u32 s14, s6, 0xe800200
	s_addc_u32 s15, s7, 0
	s_mov_b32 s2, 1
	s_mov_b64 s[6:7], 0
	s_branch .LBB0_178

.LBB0_180:
	global_load_dword v1, v0, s[12:13] sc1
	s_add_i32 s2, s2, 1
	s_mov_b64 s[20:21], -1
	s_waitcnt vmcnt(0)
	v_cmp_le_u32_e32 vcc, v2, v1
	s_orn2_b64 s[22:23], vcc, exec
	s_branch .LBB0_177

.LBB0_354:
	s_or_b64 exec, exec, s[14:15]
	v_cvt_f32_u32_e32 v5, v3
	s_waitcnt vmcnt(0)
	v_readfirstlane_b32 s0, v4
	v_sub_u32_e32 v4, 0, v3
	v_rcp_iflag_f32_e32 v5, v5
	v_add_u32_e32 v6, s0, v0
	v_mul_f32_e32 v5, 0x4f7ffffe, v5
	v_cvt_u32_f32_e32 v5, v5
	v_mul_lo_u32 v0, v4, v5
	v_mul_hi_u32 v0, v5, v0
	v_add_u32_e32 v0, v5, v0
	v_mul_hi_u32 v0, v6, v0
	v_mul_lo_u32 v4, v0, v3
	v_sub_u32_e32 v4, v6, v4
	v_add_u32_e32 v5, 1, v0
	v_cmp_ge_u32_e32 vcc, v4, v3
	s_nop 1
	v_cndmask_b32_e32 v0, v0, v5, vcc
	v_sub_u32_e32 v5, v4, v3
	v_cndmask_b32_e32 v4, v4, v5, vcc
	v_add_u32_e32 v5, 1, v0
	v_cmp_ge_u32_e32 vcc, v4, v3
	v_add_u32_e32 v4, 1, v6
	s_nop 0
	v_cndmask_b32_e32 v0, v0, v5, vcc
	v_mul_lo_u32 v5, v3, v0
	v_add_u32_e32 v3, v5, v3
	v_cmp_ne_u32_e32 vcc, v4, v3
	s_and_saveexec_b64 s[0:1], vcc
	s_xor_b64 s[10:11], exec, s[0:1]
	s_cbranch_execz .LBB0_368
	s_waitcnt lgkmcnt(0)
	s_add_u32 s18, s6, 0xe803400
	s_addc_u32 s19, s7, 0
	v_add_u32_e32 v0, 1, v0
	v_mul_lo_u32 v0, v0, v2
	v_mov_b32_e32 v2, 0
	global_load_dword v2, v2, s[18:19] sc1
	s_waitcnt vmcnt(0)
	v_cmp_gt_u32_e32 vcc, v0, v2
	s_and_saveexec_b64 s[14:15], vcc
	s_cbranch_execz .LBB0_367
	s_add_u32 s16, s6, 0xe800200
	s_addc_u32 s17, s7, 0
	s_mov_b32 s0, 1
	s_mov_b64 s[20:21], 0
	s_branch .LBB0_358

.LBB0_360:
	global_load_dword v2, v1, s[18:19] sc1
	s_add_i32 s0, s0, 1
	s_mov_b64 s[26:27], -1
	s_waitcnt vmcnt(0)
	v_cmp_le_u32_e32 vcc, v0, v2
	s_orn2_b64 s[24:25], vcc, exec
	s_branch .LBB0_357

.LBB0_371:
	s_or_b64 exec, exec, s[14:15]
	s_waitcnt vmcnt(0)
	v_readfirstlane_b32 s0, v3
	v_sub_u32_e32 v4, 0, v2
	s_add_u32 s10, s6, 0xe803400
	v_add_u32_e32 v3, s0, v0
	v_cvt_f32_u32_e32 v0, v2
	s_addc_u32 s11, s7, 0
	s_mov_b64 s[16:17], 0
	v_rcp_iflag_f32_e32 v0, v0
	s_nop 0
	v_mul_f32_e32 v0, 0x4f7ffffe, v0
	v_cvt_u32_f32_e32 v0, v0
	v_mul_lo_u32 v4, v4, v0
	v_mul_hi_u32 v4, v0, v4
	v_add_u32_e32 v0, v0, v4
	v_mul_hi_u32 v0, v3, v0
	v_mul_lo_u32 v4, v0, v2
	v_sub_u32_e32 v4, v3, v4
	v_cmp_ge_u32_e32 vcc, v4, v2
	v_add_u32_e32 v5, 1, v0
	v_add_u32_e32 v3, 1, v3
	v_cndmask_b32_e32 v0, v0, v5, vcc
	v_sub_u32_e32 v5, v4, v2
	v_cndmask_b32_e32 v4, v4, v5, vcc
	v_cmp_ge_u32_e32 vcc, v4, v2
	v_add_u32_e32 v4, 1, v0
	s_nop 0
	v_cndmask_b32_e32 v0, v0, v4, vcc
	v_mul_lo_u32 v4, v2, v0
	v_add_u32_e32 v2, v4, v2
	v_cmp_ne_u32_e32 vcc, v3, v2
	v_mov_b32_e32 v0, v2
	v_mov_b64_e32 v[2:3], s[10:11]
	s_and_saveexec_b64 s[14:15], vcc
	s_cbranch_execz .LBB0_383
	global_load_dword v2, v1, s[10:11] sc1
	s_mov_b64 s[20:21], 0
	s_waitcnt vmcnt(0)
	v_cmp_gt_u32_e32 vcc, v0, v2
	s_and_saveexec_b64 s[18:19], vcc
	s_cbranch_execz .LBB0_382
	s_add_u32 s16, s6, 0xe800200
	s_addc_u32 s17, s7, 0
	s_mov_b32 s0, 1
	s_mov_b64 s[6:7], 0
	s_branch .LBB0_375

.LBB0_377:
	global_load_dword v2, v1, s[10:11] sc1
	s_add_i32 s0, s0, 1
	s_mov_b64 s[24:25], -1
	s_waitcnt vmcnt(0)
	v_cmp_le_u32_e32 vcc, v0, v2
	s_orn2_b64 s[22:23], vcc, exec
	s_branch .LBB0_374

.LBB0_480:
	s_or_b64 exec, exec, s[12:13]
	v_cvt_f32_u32_e32 v5, v3
	s_waitcnt vmcnt(0)
	v_readfirstlane_b32 s0, v4
	v_sub_u32_e32 v4, 0, v3
	v_rcp_iflag_f32_e32 v5, v5
	v_add_u32_e32 v6, s0, v0
	v_mul_f32_e32 v5, 0x4f7ffffe, v5
	v_cvt_u32_f32_e32 v5, v5
	v_mul_lo_u32 v0, v4, v5
	v_mul_hi_u32 v0, v5, v0
	v_add_u32_e32 v0, v5, v0
	v_mul_hi_u32 v0, v6, v0
	v_mul_lo_u32 v4, v0, v3
	v_sub_u32_e32 v4, v6, v4
	v_add_u32_e32 v5, 1, v0
	v_cmp_ge_u32_e32 vcc, v4, v3
	s_nop 1
	v_cndmask_b32_e32 v0, v0, v5, vcc
	v_sub_u32_e32 v5, v4, v3
	v_cndmask_b32_e32 v4, v4, v5, vcc
	v_add_u32_e32 v5, 1, v0
	v_cmp_ge_u32_e32 vcc, v4, v3
	v_add_u32_e32 v4, 1, v6
	s_nop 0
	v_cndmask_b32_e32 v0, v0, v5, vcc
	v_mul_lo_u32 v5, v3, v0
	v_add_u32_e32 v3, v5, v3
	v_cmp_ne_u32_e32 vcc, v4, v3
	s_and_saveexec_b64 s[0:1], vcc
	s_xor_b64 s[10:11], exec, s[0:1]
	s_cbranch_execz .LBB0_494
	s_waitcnt lgkmcnt(0)
	s_add_u32 s16, s6, 0xe803400
	s_addc_u32 s17, s7, 0
	v_add_u32_e32 v0, 1, v0
	v_mul_lo_u32 v0, v0, v2
	v_mov_b32_e32 v2, 0
	global_load_dword v2, v2, s[16:17] sc1
	s_waitcnt vmcnt(0)
	v_cmp_gt_u32_e32 vcc, v0, v2
	s_and_saveexec_b64 s[12:13], vcc
	s_cbranch_execz .LBB0_493
	s_add_u32 s14, s6, 0xe800200
	s_addc_u32 s15, s7, 0
	s_mov_b32 s0, 1
	s_mov_b64 s[18:19], 0
	s_branch .LBB0_484

.LBB0_486:
	global_load_dword v2, v1, s[16:17] sc1
	s_add_i32 s0, s0, 1
	s_mov_b64 s[24:25], -1
	s_waitcnt vmcnt(0)
	v_cmp_le_u32_e32 vcc, v0, v2
	s_orn2_b64 s[22:23], vcc, exec
	s_branch .LBB0_483

.LBB0_497:
	s_or_b64 exec, exec, s[12:13]
	s_waitcnt vmcnt(0)
	v_readfirstlane_b32 s0, v3
	v_sub_u32_e32 v4, 0, v2
	s_add_u32 s10, s6, 0xe803400
	v_add_u32_e32 v3, s0, v0
	v_cvt_f32_u32_e32 v0, v2
	s_addc_u32 s11, s7, 0
	s_mov_b64 s[14:15], 0
	v_rcp_iflag_f32_e32 v0, v0
	s_nop 0
	v_mul_f32_e32 v0, 0x4f7ffffe, v0
	v_cvt_u32_f32_e32 v0, v0
	v_mul_lo_u32 v4, v4, v0
	v_mul_hi_u32 v4, v0, v4
	v_add_u32_e32 v0, v0, v4
	v_mul_hi_u32 v0, v3, v0
	v_mul_lo_u32 v4, v0, v2
	v_sub_u32_e32 v4, v3, v4
	v_cmp_ge_u32_e32 vcc, v4, v2
	v_add_u32_e32 v5, 1, v0
	v_add_u32_e32 v3, 1, v3
	v_cndmask_b32_e32 v0, v0, v5, vcc
	v_sub_u32_e32 v5, v4, v2
	v_cndmask_b32_e32 v4, v4, v5, vcc
	v_cmp_ge_u32_e32 vcc, v4, v2
	v_add_u32_e32 v4, 1, v0
	s_nop 0
	v_cndmask_b32_e32 v0, v0, v4, vcc
	v_mul_lo_u32 v4, v2, v0
	v_add_u32_e32 v2, v4, v2
	v_cmp_ne_u32_e32 vcc, v3, v2
	v_mov_b32_e32 v0, v2
	v_mov_b64_e32 v[2:3], s[10:11]
	s_and_saveexec_b64 s[12:13], vcc
	s_cbranch_execz .LBB0_509
	global_load_dword v2, v1, s[10:11] sc1
	s_mov_b64 s[18:19], 0
	s_waitcnt vmcnt(0)
	v_cmp_gt_u32_e32 vcc, v0, v2
	s_and_saveexec_b64 s[16:17], vcc
	s_cbranch_execz .LBB0_508
	s_add_u32 s14, s6, 0xe800200
	s_addc_u32 s15, s7, 0
	s_mov_b32 s0, 1
	s_mov_b64 s[6:7], 0
	s_branch .LBB0_501

.LBB0_503:
	global_load_dword v2, v1, s[10:11] sc1
	s_add_i32 s0, s0, 1
	s_mov_b64 s[22:23], -1
	s_waitcnt vmcnt(0)
	v_cmp_le_u32_e32 vcc, v0, v2
	s_orn2_b64 s[20:21], vcc, exec
	s_branch .LBB0_500

.LBB0_1219:
	s_or_b64 exec, exec, s[14:15]
	v_cvt_f32_u32_e32 v5, v3
	s_waitcnt vmcnt(0)
	v_readfirstlane_b32 s0, v4
	v_sub_u32_e32 v4, 0, v3
	v_rcp_iflag_f32_e32 v5, v5
	v_add_u32_e32 v6, s0, v0
	v_mul_f32_e32 v5, 0x4f7ffffe, v5
	v_cvt_u32_f32_e32 v5, v5
	v_mul_lo_u32 v0, v4, v5
	v_mul_hi_u32 v0, v5, v0
	v_add_u32_e32 v0, v5, v0
	v_mul_hi_u32 v0, v6, v0
	v_mul_lo_u32 v4, v0, v3
	v_sub_u32_e32 v4, v6, v4
	v_add_u32_e32 v5, 1, v0
	v_cmp_ge_u32_e32 vcc, v4, v3
	s_nop 1
	v_cndmask_b32_e32 v0, v0, v5, vcc
	v_sub_u32_e32 v5, v4, v3
	v_cndmask_b32_e32 v4, v4, v5, vcc
	v_add_u32_e32 v5, 1, v0
	v_cmp_ge_u32_e32 vcc, v4, v3
	v_add_u32_e32 v4, 1, v6
	s_nop 0
	v_cndmask_b32_e32 v0, v0, v5, vcc
	v_mul_lo_u32 v5, v3, v0
	v_add_u32_e32 v3, v5, v3
	v_cmp_ne_u32_e32 vcc, v4, v3
	s_and_saveexec_b64 s[0:1], vcc
	s_xor_b64 s[12:13], exec, s[0:1]
	s_cbranch_execz .LBB0_1233
	s_waitcnt lgkmcnt(0)
	s_add_u32 s18, s8, 0xe803400
	s_addc_u32 s19, s9, 0
	v_add_u32_e32 v0, 1, v0
	v_mul_lo_u32 v0, v0, v2
	v_mov_b32_e32 v2, 0
	global_load_dword v2, v2, s[18:19] sc1
	s_waitcnt vmcnt(0)
	v_cmp_gt_u32_e32 vcc, v0, v2
	s_and_saveexec_b64 s[14:15], vcc
	s_cbranch_execz .LBB0_1232
	s_add_u32 s16, s8, 0xe800200
	s_addc_u32 s17, s9, 0
	s_mov_b32 s0, 1
	s_mov_b64 s[20:21], 0
	s_branch .LBB0_1223

.LBB0_1236:
	s_or_b64 exec, exec, s[14:15]
	s_waitcnt vmcnt(0)
	v_readfirstlane_b32 s0, v3
	v_sub_u32_e32 v4, 0, v2
	s_add_u32 s12, s8, 0xe803400
	v_add_u32_e32 v3, s0, v0
	v_cvt_f32_u32_e32 v0, v2
	s_addc_u32 s13, s9, 0
	s_mov_b64 s[16:17], 0
	v_rcp_iflag_f32_e32 v0, v0
	s_nop 0
	v_mul_f32_e32 v0, 0x4f7ffffe, v0
	v_cvt_u32_f32_e32 v0, v0
	v_mul_lo_u32 v4, v4, v0
	v_mul_hi_u32 v4, v0, v4
	v_add_u32_e32 v0, v0, v4
	v_mul_hi_u32 v0, v3, v0
	v_mul_lo_u32 v4, v0, v2
	v_sub_u32_e32 v4, v3, v4
	v_cmp_ge_u32_e32 vcc, v4, v2
	v_add_u32_e32 v5, 1, v0
	v_add_u32_e32 v3, 1, v3
	v_cndmask_b32_e32 v0, v0, v5, vcc
	v_sub_u32_e32 v5, v4, v2
	v_cndmask_b32_e32 v4, v4, v5, vcc
	v_cmp_ge_u32_e32 vcc, v4, v2
	v_add_u32_e32 v4, 1, v0
	s_nop 0
	v_cndmask_b32_e32 v0, v0, v4, vcc
	v_mul_lo_u32 v4, v2, v0
	v_add_u32_e32 v2, v4, v2
	v_cmp_ne_u32_e32 vcc, v3, v2
	v_mov_b32_e32 v0, v2
	v_mov_b64_e32 v[2:3], s[12:13]
	s_and_saveexec_b64 s[14:15], vcc
	s_cbranch_execz .LBB0_1248
	global_load_dword v2, v1, s[12:13] sc1
	s_mov_b64 s[20:21], 0
	s_waitcnt vmcnt(0)
	v_cmp_gt_u32_e32 vcc, v0, v2
	s_and_saveexec_b64 s[18:19], vcc
	s_cbranch_execz .LBB0_1247
	s_add_u32 s16, s8, 0xe800200
	s_addc_u32 s17, s9, 0
	s_mov_b32 s0, 1
	s_mov_b64 s[8:9], 0
	s_branch .LBB0_1240

.LBB0_1242:
	global_load_dword v2, v1, s[12:13] sc1
	s_add_i32 s0, s0, 1
	s_mov_b64 s[24:25], -1
	s_waitcnt vmcnt(0)
	v_cmp_le_u32_e32 vcc, v0, v2
	s_orn2_b64 s[22:23], vcc, exec
	s_branch .LBB0_1239
